# SSD setup: the ten x-conv weight quads staged to LDS in one load batch instead of four round trips
# speedup vs baseline: 1.0049x; 1.0049x over previous
; __device__ __forceinline__ int lane_fresh() { int l; asm volatile("v_mbcnt_lo_u32_b32 %0, -1, 0\n\tv_mbcnt_hi_u32_b32 %0, -1, %0" : "=v"(l)); return l; }
; __device__ __forceinline__ void ssd_prompt_item(const Params& p, int item, const int wv) {
;   const int lane = lane_fresh(), wid = wv, tid = wv * 64 + lane, fr = lane & 15, fq = lane >> 4;
;   const int h = item & 15, b = item >> 4, g = h >> 3;
;   char* ws = p.ws;
;   u16* C_l = (u16*)g_shm;
;   u16* B_l = C_l + 128 * 136;
;   u16* G_l = B_l;
;   u16* BT_l = B_l + 128 * 136;
;   u16* xT_l = BT_l + 128 * 136;
;   u16* xw_l = xT_l + 64 * 136;
;   u16* h_l = xw_l + 64 * 136;
;   float* acum_l = (float*)(h_l + 64 * 136);
;   float* dt_l = acum_l + 128;
;   const u16* XBC = (const u16*)(ws + OFF_XBC);
;   const u16* ZS = (const u16*)(ws + OFF_ZS);
;   const float* DT = (const float*)(ws + OFF_DT);
;   u16* Y = (u16*)((char*)p.out + OOFF_XN);
;   float* YPS = (float*)(ws + OFF_YPS);
;   const float Ah = -__expf(p.in[16][h]);
;   const float Dh = p.in[17][h];
;   const float* convw = p.in[13];
;   const float* convb = p.in[14];
;   const int cc = tid & 31, rg = tid >> 5;
;   const int colbc = (cc < 16) ? (1024 + g * 128 + cc * 8) : (1280 + g * 128 + (cc - 16) * 8);
;   const int xc = tid & 7, xr = tid >> 3;
;   const int colx = h * 64 + xc * 8;
;   const int j0 = rg * 8;
;   f32x4 hacc[4];
; #pragma unroll
;   for (int pb = 0; pb < 4; ++pb) hacc[pb] = (f32x4){0.f, 0.f, 0.f, 0.f};
;   u32x4 u[11], ux[5];
;   float a0 = 0.f, a1 = 0.f;
.LBB0_568:
	v_writelane_b32 v250, s68, 22
	s_and_b32 s19, s68, 0x7f
	v_writelane_b32 v250, s19, 23
	v_writelane_b32 v250, s45, 24
	v_writelane_b32 v250, s44, 25
	s_lshl_b32 s19, s45, 7
	v_writelane_b32 v250, s40, 26
	v_ashrrev_i32_e32 v77, 4, v71
	s_and_b32 s87, s19, 0x3800
	s_and_b32 s19, s44, 15
	s_waitcnt vmcnt(0)
	v_mul_f32_e32 v69, 0x3fb8aa3b, v69
	v_lshlrev_b32_e32 v194, 3, v77
	v_readlane_b32 s4, v250, 5
	s_lshl_b32 s86, s44, 3
	s_and_b32 s85, s40, 7
	s_lshl_b32 s84, s19, 7
	v_exp_f32_e32 v193, v69
	v_cndmask_b32_e64 v56, 0, v56, s[6:7]
	v_cndmask_b32_e64 v57, 0, v57, s[6:7]
	v_cndmask_b32_e64 v58, 0, v58, s[6:7]
	v_cndmask_b32_e64 v59, 0, v59, s[6:7]
	v_cndmask_b32_e64 v60, 0, v60, s[6:7]
	v_cndmask_b32_e64 v61, 0, v61, s[6:7]
	v_cndmask_b32_e64 v62, 0, v62, s[6:7]
	v_cndmask_b32_e64 v63, 0, v63, s[6:7]
	v_add_u32_e32 v69, s4, v194
	v_readlane_b32 s4, v250, 10
	v_cmp_gt_i32_e64 s[6:7], 1, v71
	v_cndmask_b32_e64 v44, 0, v44, s[10:11]
	v_cndmask_b32_e64 v45, 0, v45, s[10:11]
	v_cndmask_b32_e64 v46, 0, v46, s[10:11]
	v_cndmask_b32_e64 v47, 0, v47, s[10:11]
	v_cndmask_b32_e64 v48, 0, v48, s[8:9]
	v_cndmask_b32_e64 v49, 0, v49, s[8:9]
	v_cndmask_b32_e64 v50, 0, v50, s[8:9]
	v_cndmask_b32_e64 v51, 0, v51, s[8:9]
	v_cndmask_b32_e64 v52, 0, v52, s[8:9]
	v_cndmask_b32_e64 v53, 0, v53, s[8:9]
	v_cndmask_b32_e64 v54, 0, v54, s[8:9]
	v_cndmask_b32_e64 v55, 0, v55, s[8:9]
	v_readlane_b32 s8, v250, 14
	v_readlane_b32 s5, v250, 11
	s_add_u32 s12, s4, s18
	v_readlane_b32 s90, v250, 19
	v_readlane_b32 s11, v250, 16
	v_readlane_b32 s18, v250, 17
	v_readlane_b32 s19, v250, 18
	v_readlane_b32 s10, v250, 15
	v_writelane_b32 v250, s6, 27
	v_lshlrev_b32_e32 v87, 2, v71
	s_movk_i32 s9, 0x110
	v_writelane_b32 v250, s7, 28
	v_cmp_gt_i32_e64 s[6:7], 2, v71
	v_lshlrev_b32_e32 v142, 2, v75
	s_addc_u32 s13, s5, 0
	v_writelane_b32 v250, s6, 29
	v_and_b32_e32 v196, -16, v71
	v_lshrrev_b32_e32 v79, 4, v64
	v_writelane_b32 v250, s7, 30
	v_cmp_gt_i32_e64 s[6:7], 4, v71
	v_and_b32_e32 v80, 0x78, v65
	s_add_i32 s4, 16, 0x22000
	v_writelane_b32 v250, s6, 31
	v_lshl_add_u32 v160, v72, 4, 16
	v_mul_lo_u32 v208, v66, s9
	v_writelane_b32 v250, s7, 32
	v_cmp_gt_i32_e64 s[6:7], 8, v71
	v_and_b32_e32 v192, 15, v71
	v_lshl_add_u64 v[150:151], s[22:23], 0, v[142:143]
	v_writelane_b32 v250, s6, 33
	v_lshl_add_u64 v[152:153], s[24:25], 0, v[142:143]
	v_lshlrev_b32_e32 v142, 2, v76
	v_writelane_b32 v250, s7, 34
	v_cmp_gt_i32_e64 s[6:7], 16, v71
	v_lshlrev_b32_e32 v158, 2, v77
	v_lshlrev_b32_e32 v81, 1, v80
	v_writelane_b32 v250, s6, 35
	v_add_u32_e32 v82, s4, v196
	v_and_b32_e32 v64, 16, v71
	v_writelane_b32 v250, s7, 36
	s_movk_i32 s6, 0x80
	v_bitop3_b32 v207, v87, s6, v161 bitop3:0x6c
	v_cmp_gt_i32_e64 s[6:7], 32, v71
	v_cmp_gt_u32_e64 s[4:5], 16, v71
	v_mul_u32_u24_e32 v71, 0x880, v72
	v_writelane_b32 v250, s6, 37
	v_lshlrev_b32_e32 v72, 1, v66
	v_lshl_add_u64 v[154:155], s[24:25], 0, v[142:143]
	v_lshrrev_b32_e32 v43, 5, v142
	v_and_b32_e32 v43, 7, v43
	v_mul_u32_u24_e32 v43, 0xa0, v43
	v_add_u32_e32 v43, 0x26810, v43
	v_writelane_b32 v250, s7, 38
	s_movk_i32 s6, 0xff00
	v_add3_u32 v209, v160, v208, s6
	v_mad_u64_u32 v[168:169], s[6:7], v74, s9, v[160:161]
	v_mul_lo_u32 v74, v79, s9
	v_lshl_add_u64 v[156:157], s[22:23], 0, v[142:143]
	v_or_b32_e32 v75, s90, v192
	s_mov_b64 s[24:25], 0x4800
	v_add3_u32 v210, s19, v71, v72
	v_lshlrev_b32_e32 v72, 2, v80
	v_add3_u32 v212, s8, v81, v74
	v_add3_u32 v216, s10, v81, v74
	v_or_b32_e32 v74, 2, v158
	s_movk_i32 s6, 0x440
	v_add_u32_e32 v80, 19, v158
	v_lshl_add_u64 v[166:167], v[150:151], 0, s[24:25]
	v_lshl_add_u64 v[174:175], v[156:157], 0, s[24:25]
	v_cmp_gt_i32_e64 s[24:25], v74, v75
	v_mul_lo_u32 v74, v77, s6
	v_cmp_gt_i32_e64 s[6:7], v80, v75
	v_add_u32_e32 v79, 18, v158
	v_add_u32_e32 v211, s18, v72
	v_writelane_b32 v250, s6, 39
	v_add_u32_e32 v213, s11, v72
	v_or_b32_e32 v72, 16, v72
	v_writelane_b32 v250, s7, 40
	v_cmp_gt_i32_e64 s[6:7], v79, v75
	v_add_u32_e32 v77, 17, v158
	s_mov_b64 s[22:23], 0x3000
	v_writelane_b32 v250, s6, 41
	v_add_u32_e32 v214, s18, v72
	v_add_u32_e32 v215, s11, v72
	v_or_b32_e32 v72, 3, v158
	v_writelane_b32 v250, s7, 42
	v_cmp_gt_i32_e64 s[6:7], v77, v75
	v_lshl_add_u64 v[164:165], v[150:151], 0, s[22:23]
	v_lshl_add_u64 v[172:173], v[156:157], 0, s[22:23]
	v_cmp_gt_i32_e64 s[22:23], v72, v75
	v_add_u32_e32 v72, 16, v158
	v_writelane_b32 v250, s6, 43
	v_lshlrev_b32_e32 v85, 2, v73
	v_lshl_add_u32 v197, v75, 2, s11
	v_writelane_b32 v250, s7, 44
	v_cmp_gt_i32_e64 s[6:7], v72, v75
	v_add_u32_e32 v72, 32, v158
	v_cmp_gt_i32_e64 s[42:43], v72, v75
	v_add_u32_e32 v72, 48, v158
	v_add_u32_e32 v198, s11, v196
	v_add_u32_e32 v200, s18, v85
	v_add_u32_e32 v201, s11, v85
	v_add_u32_e32 v85, s10, v196
	v_cmp_gt_i32_e64 s[10:11], v72, v75
	v_add_u32_e32 v72, 64, v158
	v_cmp_gt_i32_e64 s[58:59], v72, v75
	v_add_u32_e32 v72, 0x50, v158
	v_cmp_gt_i32_e64 s[66:67], v72, v75
	v_add_u32_e32 v72, 0x60, v158
	v_cmp_gt_i32_e64 s[74:75], v72, v75
	v_add_u32_e32 v72, 0x70, v158
	v_add_u32_e32 v68, s87, v68
	v_lshl_or_b32 v142, v67, 1, s84
	v_cmp_gt_i32_e64 s[82:83], v72, v75
	v_add_u32_e32 v217, s87, v73
; __device__ __forceinline__ int lane_fresh() { int l; asm volatile("v_mbcnt_lo_u32_b32 %0, -1, 0\n\tv_mbcnt_hi_u32_b32 %0, -1, %0" : "=v"(l)); return l; }
; __device__ __forceinline__ void ssd_prompt_item(const Params& p, int item, const int wv) {
;   const int lane = lane_fresh(), wid = wv, tid = wv * 64 + lane, fr = lane & 15, fq = lane >> 4;
;   const int h = item & 15, b = item >> 4, g = h >> 3;
;   char* ws = p.ws;
;   u16* C_l = (u16*)g_shm;
;   u16* B_l = C_l + 128 * 136;
;   u16* G_l = B_l;
;   u16* BT_l = B_l + 128 * 136;
;   u16* xT_l = BT_l + 128 * 136;
;   u16* xw_l = xT_l + 64 * 136;
;   u16* h_l = xw_l + 64 * 136;
;   float* acum_l = (float*)(h_l + 64 * 136);
;   float* dt_l = acum_l + 128;
;   const u16* XBC = (const u16*)(ws + OFF_XBC);
;   const u16* ZS = (const u16*)(ws + OFF_ZS);
;   const float* DT = (const float*)(ws + OFF_DT);
;   u16* Y = (u16*)((char*)p.out + OOFF_XN);
;   float* YPS = (float*)(ws + OFF_YPS);
;   const float Ah = -__expf(p.in[16][h]);
;   const float Dh = p.in[17][h];
;   const float* convw = p.in[13];
;   const float* convb = p.in[14];
;   const int cc = tid & 31, rg = tid >> 5;
;   const int colbc = (cc < 16) ? (1024 + g * 128 + cc * 8) : (1280 + g * 128 + (cc - 16) * 8);
;   const int xc = tid & 7, xr = tid >> 3;
;   const int colx = h * 64 + xc * 8;
;   const int j0 = rg * 8;
;   f32x4 hacc[4];
; #pragma unroll
;   for (int pb = 0; pb < 4; ++pb) hacc[pb] = (f32x4){0.f, 0.f, 0.f, 0.f};
;   u32x4 u[11], ux[5];
;   float a0 = 0.f, a1 = 0.f;
;     ...
;   SSD_PREFETCH(0);
;     ...
;       f32x4 b0 = *(const f32x4*)(convb + colx), b1 = *(const f32x4*)(convb + colx + 4);
;       f32x4 w0[4], w1[4];
; #pragma unroll
;       for (int k = 0; k < 4; ++k) { w0[k] = *(const f32x4*)(convw + k * 1536 + colx); w1[k] = *(const f32x4*)(convw + k * 1536 + colx + 4); }
	v_mad_i64_i32 v[72:73], s[88:89], v68, s33, v[142:143]
	v_mul_u32_u24_e32 v71, 0x110, v67
	s_mov_b64 s[88:89], 0x730e000
	v_add_u32_e32 v67, 0x80, v68
	v_writelane_b32 v250, s6, 45
	v_add_u32_e32 v80, 35, v158
	v_lshl_add_u64 v[176:177], v[72:73], 0, s[88:89]
	v_mad_i64_i32 v[72:73], s[88:89], v67, s33, v[142:143]
	v_add_u32_e32 v67, 0x7e, v68
	v_writelane_b32 v250, s7, 46
	v_cmp_gt_i32_e64 s[6:7], v80, v75
	s_mov_b64 s[92:93], 0x72aec00
	v_mad_i64_i32 v[180:181], s[88:89], v67, s33, v[142:143]
	v_add_u32_e32 v67, 0x7c, v68
	s_add_i32 s41, s90, s41
	v_add_u32_e32 v79, 34, v158
	v_writelane_b32 v250, s6, 47
	v_lshl_add_u64 v[178:179], v[72:73], 0, s[92:93]
	v_mad_i64_i32 v[72:73], s[88:89], v67, s33, v[142:143]
	v_add_u32_e32 v142, s41, v192
	v_writelane_b32 v250, s7, 48
	v_cmp_gt_i32_e64 s[6:7], v79, v75
	v_lshlrev_b64 v[184:185], 7, v[142:143]
	v_add_u32_e32 v77, 33, v158
	v_writelane_b32 v250, s6, 49
	v_add_u32_e32 v218, s87, v66
	v_and_or_b32 v66, s86, 64, v184
	v_writelane_b32 v250, s7, 50
	v_cmp_gt_i32_e64 s[6:7], v77, v75
	v_lshl_or_b32 v184, s85, 3, v66
	v_lshlrev_b64 v[66:67], 11, v[142:143]
	v_ashrrev_i32_e32 v159, 31, v158
	v_and_b32_e32 v65, -8, v158
	v_add_u32_e32 v88, 0xfc, v87
	v_writelane_b32 v250, s6, 51
	v_add_u32_e32 v77, 49, v158
	v_add_u32_e32 v79, 50, v158
	v_add_u32_e32 v80, 51, v158
	v_or_b32_e32 v66, s84, v66
	v_lshl_add_u32 v70, v70, 2, s8
	v_mul_lo_u32 v76, v75, s9
	v_add_u32_e32 v83, s8, v196
	v_lshl_add_u32 v84, v75, 1, s8
	v_add_u32_e32 v64, v65, v64
	v_and_b32_e32 v202, 0xfc, v88
	v_add_u32_e32 v88, 0xf8, v87
	v_writelane_b32 v250, s7, 52
	v_cmp_gt_i32_e64 s[44:45], v80, v75
	v_cmp_gt_i32_e64 s[6:7], v79, v75
	v_cmp_gt_i32_e64 s[8:9], v77, v75
	v_add_u32_e32 v77, 0x41, v158
	v_add_u32_e32 v79, 0x42, v158
	v_add_u32_e32 v80, 0x43, v158
	v_lshl_add_u64 v[182:183], v[72:73], 0, s[92:93]
	v_lshl_add_u64 v[72:73], v[158:159], 1, v[66:67]
	s_mov_b64 s[84:85], 0x526e040
	v_ashrrev_i32_e32 v65, 31, v64
	v_and_b32_e32 v203, 0xfc, v88
	v_add_u32_e32 v88, 0xf0, v87
	v_cmp_gt_i32_e64 s[52:53], v80, v75
	v_cmp_gt_i32_e64 s[54:55], v79, v75
	v_cmp_gt_i32_e64 s[56:57], v77, v75
	v_add_u32_e32 v77, 0x51, v158
	v_add_u32_e32 v79, 0x52, v158
	v_add_u32_e32 v80, 0x53, v158
	v_lshl_add_u64 v[186:187], v[72:73], 0, s[84:85]
	v_readlane_b32 s84, v250, 12
	v_and_b32_e32 v204, 0xfc, v88
	v_add_u32_e32 v88, 0xe0, v87
	v_cmp_gt_i32_e64 s[60:61], v80, v75
	v_cmp_gt_i32_e64 s[62:63], v79, v75
	v_cmp_gt_i32_e64 s[64:65], v77, v75
	v_add_u32_e32 v77, 0x61, v158
	v_add_u32_e32 v79, 0x62, v158
	v_add_u32_e32 v80, 0x63, v158
	v_lshl_add_u64 v[64:65], v[64:65], 1, v[66:67]
	v_readlane_b32 s85, v250, 13
	v_add_u32_e32 v195, 16, v76
	v_add_u32_e32 v78, 16, v196
	v_add_u32_e32 v76, s19, v76
	v_mul_u32_u24_e32 v86, 0x110, v192
	v_and_b32_e32 v205, 0xfc, v88
	v_add_u32_e32 v88, 0xc0, v87
	s_mov_b64 s[20:21], 0x1800
	v_cmp_gt_i32_e64 s[68:69], v80, v75
	v_cmp_gt_i32_e64 s[70:71], v79, v75
	v_cmp_gt_i32_e64 s[72:73], v77, v75
	v_add_u32_e32 v77, 0x71, v158
	v_add_u32_e32 v79, 0x72, v158
	v_add_u32_e32 v80, 0x73, v158
	v_lshl_add_u64 v[188:189], s[84:85], 0, v[64:65]
	v_mov_b32_e32 v64, 0
	s_mov_b32 s40, 0
	v_add_u32_e32 v199, s18, v196
	v_and_b32_e32 v206, 0xfc, v88
	v_lshl_add_u64 v[162:163], v[150:151], 0, s[20:21]
	v_add_u32_e32 v169, 0xffffff00, v168
	v_lshl_add_u64 v[170:171], v[156:157], 0, s[20:21]
	v_cmp_gt_i32_e64 s[18:19], v158, v75
	v_cmp_lt_i32_e64 s[20:21], v158, v75
	v_mov_b32_e32 v145, v144
	v_cmp_gt_i32_e64 s[76:77], v80, v75
	v_cmp_gt_i32_e64 s[78:79], v79, v75
	v_cmp_gt_i32_e64 s[80:81], v77, v75
	v_add_u32_e32 v219, v69, v86
	v_add_u32_e32 v220, v70, v71
	v_add_u32_e32 v221, v76, v196
	v_add_u32_e32 v222, v85, v86
	v_add_u32_e32 v223, v78, v86
	v_add_u32_e32 v224, v82, v86
	v_add_u32_e32 v225, v83, v86
	v_add_u32_e32 v226, v84, v74
	v_mov_b32_e32 v65, v64
	v_mov_b32_e32 v66, v64
	v_mov_b32_e32 v67, v64
	v_mov_b32_e32 v76, v64
	v_mov_b32_e32 v77, v64
	v_mov_b32_e32 v78, v64
	v_mov_b32_e32 v79, v64
	v_mov_b32_e32 v72, v64
	v_mov_b32_e32 v73, v64
	v_mov_b32_e32 v74, v64
	v_mov_b32_e32 v75, v64
	v_mov_b32_e32 v68, v64
	v_mov_b32_e32 v69, v64
	v_mov_b32_e32 v70, v64
	v_mov_b32_e32 v71, v64
	global_load_dwordx4 v[32:35], v[154:155], off offset:16
	global_load_dwordx4 v[36:39], v[154:155], off
	global_load_dwordx4 v[244:247], v[156:157], off offset:16
	global_load_dwordx4 v[150:153], v[156:157], off
	global_load_dwordx4 v[162:165], v[170:171], off offset:16
	global_load_dwordx4 v[236:239], v[170:171], off
	global_load_dwordx4 v[80:83], v[172:173], off offset:16
	global_load_dwordx4 v[84:87], v[172:173], off
	global_load_dwordx4 v[88:91], v[174:175], off offset:16
	global_load_dwordx4 v[92:95], v[174:175], off
	s_waitcnt vmcnt(0)
	ds_write_b128 v43, v[32:35] offset:0
	ds_write_b128 v43, v[36:39] offset:16
	ds_write_b128 v43, v[244:247] offset:32
	ds_write_b128 v43, v[150:153] offset:48
	ds_write_b128 v43, v[162:165] offset:64
	ds_write_b128 v43, v[236:239] offset:80
	ds_write_b128 v43, v[80:83] offset:96
	ds_write_b128 v43, v[84:87] offset:112
	ds_write_b128 v43, v[88:91] offset:128
	ds_write_b128 v43, v[92:95] offset:144
	s_waitcnt lgkmcnt(0)
	s_branch .LBB0_570
